# attention main loops: cross-half row max by v_permlane32_swap instead of a recomputed-address ds_bpermute round trip (instruction selection lever)
# speedup vs baseline: 1.0062x; 1.0062x over previous
; __device__ __forceinline__ void attn_unit(LAS unsigned char* lds, int b, int h, int qb, const bf16_t* Q, const bf16_t* KF, const bf16_t* VT,
;                                           const float* gout, bf16_t* MIXED, int wave, int lane) {
;     ...
;             float mt = sacc[0][0];
; #pragma unroll
;             for (int kb = 0; kb < 2; ++kb)
; #pragma unroll
;                 for (int i = 0; i < 16; ++i) mt = fmaxf(mt, sacc[kb][i]);
;             mt = fmaxf(mt, __shfl_xor(mt, 32));
;             __builtin_amdgcn_sched_barrier(0);
;             if (__builtin_amdgcn_ballot_w64(mt > m_run + 8.f) != 0ull) {
;                 const float mn = fmaxf(m_run, mt);
;                 const float alpha = __builtin_amdgcn_exp2f(m_run - mn);
;                 m_run = mn;
;                 l_run *= alpha;
; #pragma unroll
;                 for (int db = 0; db < 4; ++db)
; #pragma unroll
;                     for (int i = 0; i < 16; ++i) asm volatile("v_mul_f32 %0, %0, %1" : "+v"(oacc[db][i]) : "v"(alpha));
;             }
.LBB0_455:
	v_max_f32_e32 v108, v65, v65
	v_max_f32_e32 v109, v64, v64
	v_max_f32_e32 v108, v109, v108
	v_max3_f32 v108, v108, v66, v67
	v_max3_f32 v108, v108, v68, v69
	v_max3_f32 v108, v108, v70, v71
	v_max3_f32 v108, v108, v72, v73
	v_max3_f32 v108, v108, v74, v75
	v_max3_f32 v108, v108, v76, v77
	v_max3_f32 v108, v108, v78, v79
	v_max3_f32 v108, v108, v80, v81
	v_max3_f32 v108, v108, v82, v83
	v_max3_f32 v108, v108, v84, v85
	v_max3_f32 v108, v108, v86, v87
	v_max3_f32 v108, v108, v88, v89
	v_max3_f32 v108, v108, v90, v91
	v_max3_f32 v108, v108, v92, v93
	v_max3_f32 v108, v108, v94, v95
	v_mov_b32_e32 v109, v108
	s_nop 1
	v_permlane32_swap_b32_e32 v109, v108
	v_max_f32_e32 v108, v108, v109
	v_add_f32_e32 v109, 0x41000000, v220
	v_cmp_gt_f32_e32 vcc, v108, v109
	s_cbranch_vccz .LBB0_457
	v_max_f32_e32 v108, v108, v108
	v_max_f32_e32 v109, v220, v220
	v_max_f32_e32 v108, v109, v108
	v_sub_f32_e32 v109, v220, v108
	v_exp_f32_e32 v109, v109
	v_mov_b32_e32 v220, v108
	v_mul_f32 v48, v48, v109
	v_mul_f32 v49, v49, v109
	v_mul_f32_e32 v211, v211, v109
	v_mul_f32 v50, v50, v109
	v_mul_f32 v51, v51, v109
	v_mul_f32 v52, v52, v109
	v_mul_f32 v53, v53, v109
	v_mul_f32 v54, v54, v109
	v_mul_f32 v55, v55, v109
	v_mul_f32 v56, v56, v109
	v_mul_f32 v57, v57, v109
	v_mul_f32 v58, v58, v109
	v_mul_f32 v59, v59, v109
	v_mul_f32 v60, v60, v109
	v_mul_f32 v61, v61, v109
	v_mul_f32 v62, v62, v109
	v_mul_f32 v63, v63, v109
	v_mul_f32 v32, v32, v109
	v_mul_f32 v33, v33, v109
	v_mul_f32 v34, v34, v109
	v_mul_f32 v35, v35, v109
	v_mul_f32 v36, v36, v109
	v_mul_f32 v37, v37, v109
	v_mul_f32 v38, v38, v109
	v_mul_f32 v39, v39, v109
	v_mul_f32 v40, v40, v109
	v_mul_f32 v41, v41, v109
	v_mul_f32 v42, v42, v109
	v_mul_f32 v43, v43, v109
	v_mul_f32 v44, v44, v109
	v_mul_f32 v45, v45, v109
	v_mul_f32 v46, v46, v109
	v_mul_f32 v47, v47, v109
	v_mul_f32 v16, v16, v109
	v_mul_f32 v17, v17, v109
	v_mul_f32 v18, v18, v109
	v_mul_f32 v19, v19, v109
	v_mul_f32 v20, v20, v109
	v_mul_f32 v21, v21, v109
	v_mul_f32 v22, v22, v109
	v_mul_f32 v23, v23, v109
	v_mul_f32 v24, v24, v109
	v_mul_f32 v25, v25, v109
	v_mul_f32 v26, v26, v109
	v_mul_f32 v27, v27, v109
	v_mul_f32 v28, v28, v109
	v_mul_f32 v29, v29, v109
	v_mul_f32 v30, v30, v109
	v_mul_f32 v31, v31, v109
	v_mul_f32 v0, v0, v109
	v_mul_f32 v1, v1, v109
	v_mul_f32 v2, v2, v109
	v_mul_f32 v3, v3, v109
	v_mul_f32 v4, v4, v109
	v_mul_f32 v5, v5, v109
	v_mul_f32 v6, v6, v109
	v_mul_f32 v7, v7, v109
	v_mul_f32 v8, v8, v109
	v_mul_f32 v9, v9, v109
	v_mul_f32 v10, v10, v109
	v_mul_f32 v11, v11, v109
	v_mul_f32 v12, v12, v109
	v_mul_f32 v13, v13, v109
	v_mul_f32 v14, v14, v109
	v_mul_f32 v15, v15, v109

; __device__ __forceinline__ void attn_unit(LAS unsigned char* lds, int b, int h, int qb, const bf16_t* Q, const bf16_t* KF, const bf16_t* VT,
;                                           const float* gout, bf16_t* MIXED, int wave, int lane) {
;     ...
;             float mt = sacc[0][0];
; #pragma unroll
;             for (int kb = 0; kb < 2; ++kb)
; #pragma unroll
;                 for (int i = 0; i < 16; ++i) mt = fmaxf(mt, sacc[kb][i]);
;             mt = fmaxf(mt, __shfl_xor(mt, 32));
;             __builtin_amdgcn_sched_barrier(0);
;             if (__builtin_amdgcn_ballot_w64(mt > m_run + 8.f) != 0ull) {
;                 const float mn = fmaxf(m_run, mt);
;                 const float alpha = __builtin_amdgcn_exp2f(m_run - mn);
;                 m_run = mn;
;                 l_run *= alpha;
; #pragma unroll
;                 for (int db = 0; db < 4; ++db)
; #pragma unroll
;                     for (int i = 0; i < 16; ++i) asm volatile("v_mul_f32 %0, %0, %1" : "+v"(oacc[db][i]) : "v"(alpha));
;             }
.LBB0_508:
	v_max_f32_e32 v110, v65, v65
	v_max_f32_e32 v111, v64, v64
	v_max_f32_e32 v110, v111, v110
	v_max3_f32 v110, v110, v66, v67
	v_max3_f32 v110, v110, v68, v69
	v_max3_f32 v110, v110, v70, v71
	v_max3_f32 v110, v110, v72, v73
	v_max3_f32 v110, v110, v74, v75
	v_max3_f32 v110, v110, v76, v77
	v_max3_f32 v110, v110, v78, v79
	v_max3_f32 v110, v110, v80, v81
	v_max3_f32 v110, v110, v82, v83
	v_max3_f32 v110, v110, v84, v85
	v_max3_f32 v110, v110, v86, v87
	v_max3_f32 v110, v110, v88, v89
	v_max3_f32 v110, v110, v90, v91
	v_max3_f32 v110, v110, v92, v93
	v_max3_f32 v110, v110, v94, v95
	v_mov_b32_e32 v111, v110
	s_nop 1
	v_permlane32_swap_b32_e32 v111, v110
	v_max_f32_e32 v110, v110, v111
	v_add_f32_e32 v111, 0x41000000, v220
	v_cmp_gt_f32_e32 vcc, v110, v111
	s_cbranch_vccz .LBB0_510
	v_max_f32_e32 v110, v110, v110
	v_max_f32_e32 v111, v220, v220
	v_max_f32_e32 v110, v111, v110
	v_sub_f32_e32 v111, v220, v110
	v_exp_f32_e32 v111, v111
	v_mov_b32_e32 v220, v110
	v_mul_f32 v48, v48, v111
	v_mul_f32 v49, v49, v111
	v_mul_f32_e32 v211, v211, v111
	v_mul_f32 v50, v50, v111
	v_mul_f32 v51, v51, v111
	v_mul_f32 v52, v52, v111
	v_mul_f32 v53, v53, v111
	v_mul_f32 v54, v54, v111
	v_mul_f32 v55, v55, v111
	v_mul_f32 v56, v56, v111
	v_mul_f32 v57, v57, v111
	v_mul_f32 v58, v58, v111
	v_mul_f32 v59, v59, v111
	v_mul_f32 v60, v60, v111
	v_mul_f32 v61, v61, v111
	v_mul_f32 v62, v62, v111
	v_mul_f32 v63, v63, v111
	v_mul_f32 v32, v32, v111
	v_mul_f32 v33, v33, v111
	v_mul_f32 v34, v34, v111
	v_mul_f32 v35, v35, v111
	v_mul_f32 v36, v36, v111
	v_mul_f32 v37, v37, v111
	v_mul_f32 v38, v38, v111
	v_mul_f32 v39, v39, v111
	v_mul_f32 v40, v40, v111
	v_mul_f32 v41, v41, v111
	v_mul_f32 v42, v42, v111
	v_mul_f32 v43, v43, v111
	v_mul_f32 v44, v44, v111
	v_mul_f32 v45, v45, v111
	v_mul_f32 v46, v46, v111
	v_mul_f32 v47, v47, v111
	v_mul_f32 v16, v16, v111
	v_mul_f32 v17, v17, v111
	v_mul_f32 v18, v18, v111
	v_mul_f32 v19, v19, v111
	v_mul_f32 v20, v20, v111
	v_mul_f32 v21, v21, v111
	v_mul_f32 v22, v22, v111
	v_mul_f32 v23, v23, v111
	v_mul_f32 v24, v24, v111
	v_mul_f32 v25, v25, v111
	v_mul_f32 v26, v26, v111
	v_mul_f32 v27, v27, v111
	v_mul_f32 v28, v28, v111
	v_mul_f32 v29, v29, v111
	v_mul_f32 v30, v30, v111
	v_mul_f32 v31, v31, v111
	v_mul_f32 v0, v0, v111
	v_mul_f32 v1, v1, v111
	v_mul_f32 v2, v2, v111
	v_mul_f32 v3, v3, v111
	v_mul_f32 v4, v4, v111
	v_mul_f32 v5, v5, v111
	v_mul_f32 v6, v6, v111
	v_mul_f32 v7, v7, v111
	v_mul_f32 v8, v8, v111
	v_mul_f32 v9, v9, v111
	v_mul_f32 v10, v10, v111
	v_mul_f32 v11, v11, v111
	v_mul_f32 v12, v12, v111
	v_mul_f32 v13, v13, v111
	v_mul_f32 v14, v14, v111
	v_mul_f32 v15, v15, v111
